# grid barrier: cache invalidates moved off the release path (each workgroup invalidates on arrival; XCD leader invalidates L2 right after its write-back)
# speedup vs baseline: 1.0327x; 1.0243x over previous
; __device__ __forceinline__ unsigned xb_add(unsigned* p, unsigned v) { return __hip_atomic_fetch_add(p, v, __ATOMIC_RELAXED, __HIP_MEMORY_SCOPE_AGENT); }
; __device__ __forceinline__ void xcd_barrier(const XcdBarrier& b) {
;     ...
;             __builtin_amdgcn_fence(__ATOMIC_ACQUIRE, "agent");
;             xb_add(&bar[XB_XGEN(b.x)], 1u);
;             asm volatile("s_waitcnt vmcnt(0)" ::: "memory");
.LBB0_115:
	s_or_b64 exec, exec, s[0:1]
	v_readlane_b32 s0, v255, 4
	v_readlane_b32 s1, v255, 5
	s_mov_b32 s3, s1
	s_add_i32 s2, s20, 0x900
	v_writelane_b32 v255, s0, 4
	v_mov_b32_e32 v2, 1
	s_waitcnt vmcnt(0) lgkmcnt(0)
	v_writelane_b32 v255, s1, 5
	s_lshl_b64 s[0:1], s[2:3], 2
	s_add_u32 s0, s34, s0
	s_addc_u32 s1, s35, s1
	v_mov_b64_e32 v[0:1], s[0:1]
	flat_atomic_add v[0:1], v2
	s_waitcnt vmcnt(0)

; __device__ __forceinline__ unsigned xb_ld(unsigned* p)              { return __hip_atomic_load(p, __ATOMIC_RELAXED, __HIP_MEMORY_SCOPE_AGENT); }
; __device__ __forceinline__ unsigned xb_add(unsigned* p, unsigned v) { return __hip_atomic_fetch_add(p, v, __ATOMIC_RELAXED, __HIP_MEMORY_SCOPE_AGENT); }
; #define XB_SPIN(cond, bar) do { unsigned _sp = 0; while (cond) { __builtin_amdgcn_s_sleep(1); \
;     if ((++_sp & 255u) == 0u) { if (xb_ld(&(bar)[XB_TMO])) break; if (_sp > XB_SPIN_CAP) { atomicAdd(&(bar)[XB_TMO], 1u); break; } } } } while (0)
; __device__ __forceinline__ void xcd_barrier(const XcdBarrier& b) {
;     ...
;     if (threadIdx.x == 0) {
;         unsigned* bar = b.bar;
;         __builtin_amdgcn_s_waitcnt(0);
;         unsigned nloc = b.st[0], nx = b.st[1];
;         if (nloc == 0u) { xcd_barrier_complete(bar, b.x, nloc, nx); b.st[0] = nloc; b.st[1] = nx; }
;         const unsigned old = xb_add(&bar[XB_XSUB(b.x)], 1u);
;         const unsigned gen = old / nloc;
;         if (old + 1u == (gen + 1u) * nloc) {
;             __builtin_amdgcn_fence(__ATOMIC_RELEASE, "agent");
;             asm volatile("s_waitcnt vmcnt(0)" ::: "memory");
;             const unsigned og = xb_add(&bar[XB_TOP], 1u);
;             const unsigned tg = og / nx;
;             if (og + 1u == (tg + 1u) * nx) xb_add(&bar[XB_TOPGEN], 1u);
;             else XB_SPIN(xb_ld(&bar[XB_TOPGEN]) == tg, bar);
;             __builtin_amdgcn_fence(__ATOMIC_ACQUIRE, "agent");
;             xb_add(&bar[XB_XGEN(b.x)], 1u);
;             asm volatile("s_waitcnt vmcnt(0)" ::: "memory");
;         } else {
;             XB_SPIN(xb_ld(&bar[XB_XGEN(b.x)]) == gen, bar);
.LBB0_279:
	v_readlane_b32 s0, v255, 4
	s_lshl_b32 s22, s33, 6
	v_readlane_b32 s1, v255, 5
	s_mov_b32 s5, s1
	s_add_i32 s4, s22, 0x500
	v_writelane_b32 v255, s0, 4
	v_mov_b32_e32 v1, 1
	s_nop 0
	v_writelane_b32 v255, s1, 5
	s_lshl_b64 s[0:1], s[4:5], 2
	s_add_u32 s0, s34, s0
	s_addc_u32 s1, s35, s1
	v_mov_b64_e32 v[4:5], s[0:1]
	flat_atomic_add v3, v[4:5], v1 sc0
	v_cvt_f32_u32_e32 v1, v2
	v_sub_u32_e32 v4, 0, v2
	v_rcp_iflag_f32_e32 v1, v1
	s_nop 0
	v_mul_f32_e32 v1, 0x4f7ffffe, v1
	v_cvt_u32_f32_e32 v1, v1
	v_mul_lo_u32 v4, v4, v1
	v_mul_hi_u32 v4, v1, v4
	v_add_u32_e32 v1, v1, v4
	s_waitcnt vmcnt(0) lgkmcnt(0)
	v_mul_hi_u32 v1, v3, v1
	v_mul_lo_u32 v4, v1, v2
	v_sub_u32_e32 v4, v3, v4
	v_cmp_ge_u32_e32 vcc, v4, v2
	v_add_u32_e32 v5, 1, v1
	s_nop 0
	v_cndmask_b32_e32 v1, v1, v5, vcc
	v_sub_u32_e32 v5, v4, v2
	v_cndmask_b32_e32 v4, v4, v5, vcc
	v_cmp_ge_u32_e32 vcc, v4, v2
	v_add_u32_e32 v4, 1, v1
	s_nop 0
	v_cndmask_b32_e32 v1, v1, v4, vcc
	v_add_u32_e32 v4, 1, v3
	v_mad_u64_u32 v[2:3], s[0:1], v2, v1, v[2:3]
	v_cmp_ne_u32_e32 vcc, v4, v2
	s_and_saveexec_b64 s[0:1], vcc
	s_xor_b64 s[0:1], exec, s[0:1]
	s_cbranch_execz .LBB0_292
	buffer_inv sc1
	v_readlane_b32 s4, v255, 4
	v_readlane_b32 s5, v255, 5
	s_mov_b32 s7, s5
	s_add_i32 s6, s22, 0x900
	v_writelane_b32 v255, s4, 4
	s_nop 1
	v_writelane_b32 v255, s5, 5
	s_lshl_b64 s[4:5], s[6:7], 2
	s_add_u32 s6, s34, s4
	s_addc_u32 s7, s35, s5
	v_mov_b64_e32 v[2:3], s[6:7]
	flat_load_dword v0, v[2:3] sc1
	s_waitcnt vmcnt(0) lgkmcnt(0)
	v_cmp_eq_u32_e32 vcc, v0, v1
	s_and_saveexec_b64 s[4:5], vcc
	s_cbranch_execz .LBB0_291
	s_mov_b32 s23, 1
	s_mov_b64 s[8:9], 0
	s_branch .LBB0_283

; __device__ __forceinline__ unsigned xb_ld(unsigned* p)              { return __hip_atomic_load(p, __ATOMIC_RELAXED, __HIP_MEMORY_SCOPE_AGENT); }
; __device__ __forceinline__ unsigned xb_add(unsigned* p, unsigned v) { return __hip_atomic_fetch_add(p, v, __ATOMIC_RELAXED, __HIP_MEMORY_SCOPE_AGENT); }
; #define XB_SPIN(cond, bar) do { unsigned _sp = 0; while (cond) { __builtin_amdgcn_s_sleep(1); \
;     if ((++_sp & 255u) == 0u) { if (xb_ld(&(bar)[XB_TMO])) break; if (_sp > XB_SPIN_CAP) { atomicAdd(&(bar)[XB_TMO], 1u); break; } } } } while (0)
; __device__ __forceinline__ void xcd_barrier(const XcdBarrier& b) {
;     ...
;         if (old + 1u == (gen + 1u) * nloc) {
;             __builtin_amdgcn_fence(__ATOMIC_RELEASE, "agent");
;             asm volatile("s_waitcnt vmcnt(0)" ::: "memory");
;             const unsigned og = xb_add(&bar[XB_TOP], 1u);
;             const unsigned tg = og / nx;
;             if (og + 1u == (tg + 1u) * nx) xb_add(&bar[XB_TOPGEN], 1u);
;             else XB_SPIN(xb_ld(&bar[XB_TOPGEN]) == tg, bar);
;             __builtin_amdgcn_fence(__ATOMIC_ACQUIRE, "agent");
.LBB0_291:
	s_or_b64 exec, exec, s[4:5]
	s_waitcnt vmcnt(0) lgkmcnt(0)
	s_waitcnt vmcnt(0)
.LBB0_292:
	s_andn2_saveexec_b64 s[0:1], s[0:1]
	s_cbranch_execz .LBB0_308
	v_mov_b32_e32 v1, s34
	v_add_co_u32_e32 v2, vcc, 0x3000, v1
	v_mov_b32_e32 v1, s35
	buffer_wbl2 sc1
	s_waitcnt vmcnt(0)
	buffer_inv sc1
	v_addc_co_u32_e32 v3, vcc, 0, v1, vcc
	v_mov_b32_e32 v1, 1
	flat_atomic_add v1, v[2:3], v1 offset:1024 sc0
	v_cvt_f32_u32_e32 v2, v0
	v_sub_u32_e32 v3, 0, v0
	s_mov_b64 s[6:7], -1
	v_rcp_iflag_f32_e32 v2, v2
	s_nop 0
	v_mul_f32_e32 v2, 0x4f7ffffe, v2
	v_cvt_u32_f32_e32 v2, v2
	v_mul_lo_u32 v3, v3, v2
	v_mul_hi_u32 v3, v2, v3
	v_add_u32_e32 v2, v2, v3
	s_waitcnt vmcnt(0) lgkmcnt(0)
	v_mul_hi_u32 v2, v1, v2
	v_mul_lo_u32 v3, v2, v0
	v_sub_u32_e32 v3, v1, v3
	v_cmp_ge_u32_e32 vcc, v3, v0
	v_add_u32_e32 v4, 1, v2
	s_nop 0
	v_cndmask_b32_e32 v2, v2, v4, vcc
	v_sub_u32_e32 v4, v3, v0
	v_cndmask_b32_e32 v3, v3, v4, vcc
	v_cmp_ge_u32_e32 vcc, v3, v0
	v_add_u32_e32 v3, 1, v2
	s_nop 0
	v_cndmask_b32_e32 v2, v2, v3, vcc
	v_add_u32_e32 v3, 1, v1
	v_mad_u64_u32 v[0:1], s[0:1], v0, v2, v[0:1]
	s_add_u32 s0, s34, 0x3500
	s_addc_u32 s1, s35, 0
	v_cmp_ne_u32_e32 vcc, v3, v0
	v_mov_b64_e32 v[0:1], s[0:1]
	s_and_saveexec_b64 s[4:5], vcc
	s_cbranch_execz .LBB0_305
	v_mov_b64_e32 v[0:1], s[0:1]
	flat_load_dword v0, v[0:1] sc1
	s_mov_b64 s[10:11], 0
	s_waitcnt vmcnt(0) lgkmcnt(0)
	v_cmp_eq_u32_e32 vcc, v0, v2
	s_and_saveexec_b64 s[8:9], vcc
	s_cbranch_execz .LBB0_304
	s_add_u32 s6, s34, 0x200
	s_addc_u32 s7, s35, 0
	s_mov_b32 s23, 1
	s_branch .LBB0_297

; __device__ __forceinline__ unsigned xb_add(unsigned* p, unsigned v) { return __hip_atomic_fetch_add(p, v, __ATOMIC_RELAXED, __HIP_MEMORY_SCOPE_AGENT); }
; __device__ __forceinline__ void xcd_barrier(const XcdBarrier& b) {
;     ...
;             __builtin_amdgcn_fence(__ATOMIC_ACQUIRE, "agent");
;             xb_add(&bar[XB_XGEN(b.x)], 1u);
;             asm volatile("s_waitcnt vmcnt(0)" ::: "memory");
.LBB0_307:
	s_or_b64 exec, exec, s[0:1]
	v_readlane_b32 s0, v255, 4
	v_readlane_b32 s1, v255, 5
	s_mov_b32 s5, s1
	s_add_i32 s4, s22, 0x900
	v_writelane_b32 v255, s0, 4
	v_mov_b32_e32 v2, 1
	s_waitcnt vmcnt(0) lgkmcnt(0)
	v_writelane_b32 v255, s1, 5
	s_lshl_b64 s[0:1], s[4:5], 2
	s_add_u32 s0, s34, s0
	s_addc_u32 s1, s35, s1
	v_mov_b64_e32 v[0:1], s[0:1]
	flat_atomic_add v[0:1], v2
	s_waitcnt vmcnt(0)

; __device__ __forceinline__ unsigned xb_ld(unsigned* p)              { return __hip_atomic_load(p, __ATOMIC_RELAXED, __HIP_MEMORY_SCOPE_AGENT); }
; __device__ __forceinline__ unsigned xb_add(unsigned* p, unsigned v) { return __hip_atomic_fetch_add(p, v, __ATOMIC_RELAXED, __HIP_MEMORY_SCOPE_AGENT); }
; #define XB_SPIN(cond, bar) do { unsigned _sp = 0; while (cond) { __builtin_amdgcn_s_sleep(1); \
;     if ((++_sp & 255u) == 0u) { if (xb_ld(&(bar)[XB_TMO])) break; if (_sp > XB_SPIN_CAP) { atomicAdd(&(bar)[XB_TMO], 1u); break; } } } } while (0)
; __device__ __forceinline__ void xcd_barrier(const XcdBarrier& b) {
;     ...
;     if (threadIdx.x == 0) {
;         unsigned* bar = b.bar;
;         __builtin_amdgcn_s_waitcnt(0);
;         unsigned nloc = b.st[0], nx = b.st[1];
;         if (nloc == 0u) { xcd_barrier_complete(bar, b.x, nloc, nx); b.st[0] = nloc; b.st[1] = nx; }
;         const unsigned old = xb_add(&bar[XB_XSUB(b.x)], 1u);
;         const unsigned gen = old / nloc;
;         if (old + 1u == (gen + 1u) * nloc) {
;             __builtin_amdgcn_fence(__ATOMIC_RELEASE, "agent");
;             asm volatile("s_waitcnt vmcnt(0)" ::: "memory");
;             const unsigned og = xb_add(&bar[XB_TOP], 1u);
;             const unsigned tg = og / nx;
;             if (og + 1u == (tg + 1u) * nx) xb_add(&bar[XB_TOPGEN], 1u);
;             else XB_SPIN(xb_ld(&bar[XB_TOPGEN]) == tg, bar);
;             __builtin_amdgcn_fence(__ATOMIC_ACQUIRE, "agent");
;             xb_add(&bar[XB_XGEN(b.x)], 1u);
;             asm volatile("s_waitcnt vmcnt(0)" ::: "memory");
;         } else {
;             XB_SPIN(xb_ld(&bar[XB_XGEN(b.x)]) == gen, bar);
.LBB0_669:
	v_readlane_b32 s0, v255, 4
	s_lshl_b32 s20, s33, 6
	v_readlane_b32 s1, v255, 5
	s_mov_b32 s3, s1
	s_add_i32 s2, s20, 0x500
	v_writelane_b32 v255, s0, 4
	v_mov_b32_e32 v1, 1
	s_nop 0
	v_writelane_b32 v255, s1, 5
	s_lshl_b64 s[0:1], s[2:3], 2
	s_add_u32 s0, s34, s0
	s_addc_u32 s1, s35, s1
	v_mov_b64_e32 v[4:5], s[0:1]
	flat_atomic_add v3, v[4:5], v1 sc0
	v_cvt_f32_u32_e32 v1, v2
	v_sub_u32_e32 v4, 0, v2
	v_rcp_iflag_f32_e32 v1, v1
	s_nop 0
	v_mul_f32_e32 v1, 0x4f7ffffe, v1
	v_cvt_u32_f32_e32 v1, v1
	v_mul_lo_u32 v4, v4, v1
	v_mul_hi_u32 v4, v1, v4
	v_add_u32_e32 v1, v1, v4
	s_waitcnt vmcnt(0) lgkmcnt(0)
	v_mul_hi_u32 v1, v3, v1
	v_mul_lo_u32 v4, v1, v2
	v_sub_u32_e32 v4, v3, v4
	v_cmp_ge_u32_e32 vcc, v4, v2
	v_add_u32_e32 v5, 1, v1
	s_nop 0
	v_cndmask_b32_e32 v1, v1, v5, vcc
	v_sub_u32_e32 v5, v4, v2
	v_cndmask_b32_e32 v4, v4, v5, vcc
	v_cmp_ge_u32_e32 vcc, v4, v2
	v_add_u32_e32 v4, 1, v1
	s_nop 0
	v_cndmask_b32_e32 v1, v1, v4, vcc
	v_add_u32_e32 v4, 1, v3
	v_mad_u64_u32 v[2:3], s[0:1], v2, v1, v[2:3]
	v_cmp_ne_u32_e32 vcc, v4, v2
	s_and_saveexec_b64 s[0:1], vcc
	s_xor_b64 s[0:1], exec, s[0:1]
	s_cbranch_execz .LBB0_682
	buffer_inv sc1
	v_readlane_b32 s2, v255, 4
	v_readlane_b32 s3, v255, 5
	s_mov_b32 s5, s3
	s_add_i32 s4, s20, 0x900
	v_writelane_b32 v255, s2, 4
	s_nop 1
	v_writelane_b32 v255, s3, 5
	s_lshl_b64 s[2:3], s[4:5], 2
	s_add_u32 s4, s34, s2
	s_addc_u32 s5, s35, s3
	v_mov_b64_e32 v[2:3], s[4:5]
	flat_load_dword v0, v[2:3] sc1
	s_waitcnt vmcnt(0) lgkmcnt(0)
	v_cmp_eq_u32_e32 vcc, v0, v1
	s_and_saveexec_b64 s[2:3], vcc
	s_cbranch_execz .LBB0_681
	s_mov_b32 s21, 1
	s_mov_b64 s[6:7], 0
	s_branch .LBB0_673

; __device__ __forceinline__ unsigned xb_ld(unsigned* p)              { return __hip_atomic_load(p, __ATOMIC_RELAXED, __HIP_MEMORY_SCOPE_AGENT); }
; __device__ __forceinline__ unsigned xb_add(unsigned* p, unsigned v) { return __hip_atomic_fetch_add(p, v, __ATOMIC_RELAXED, __HIP_MEMORY_SCOPE_AGENT); }
; #define XB_SPIN(cond, bar) do { unsigned _sp = 0; while (cond) { __builtin_amdgcn_s_sleep(1); \
;     if ((++_sp & 255u) == 0u) { if (xb_ld(&(bar)[XB_TMO])) break; if (_sp > XB_SPIN_CAP) { atomicAdd(&(bar)[XB_TMO], 1u); break; } } } } while (0)
; __device__ __forceinline__ void xcd_barrier(const XcdBarrier& b) {
;     ...
;         if (old + 1u == (gen + 1u) * nloc) {
;             __builtin_amdgcn_fence(__ATOMIC_RELEASE, "agent");
;             asm volatile("s_waitcnt vmcnt(0)" ::: "memory");
;             const unsigned og = xb_add(&bar[XB_TOP], 1u);
;             const unsigned tg = og / nx;
;             if (og + 1u == (tg + 1u) * nx) xb_add(&bar[XB_TOPGEN], 1u);
;             else XB_SPIN(xb_ld(&bar[XB_TOPGEN]) == tg, bar);
;             __builtin_amdgcn_fence(__ATOMIC_ACQUIRE, "agent");
.LBB0_681:
	s_or_b64 exec, exec, s[2:3]
	s_waitcnt vmcnt(0) lgkmcnt(0)
	s_waitcnt vmcnt(0)
.LBB0_682:
	s_andn2_saveexec_b64 s[0:1], s[0:1]
	s_cbranch_execz .LBB0_698
	v_mov_b32_e32 v1, s34
	v_add_co_u32_e32 v2, vcc, 0x3000, v1
	v_mov_b32_e32 v1, s35
	buffer_wbl2 sc1
	s_waitcnt vmcnt(0)
	buffer_inv sc1
	v_addc_co_u32_e32 v3, vcc, 0, v1, vcc
	v_mov_b32_e32 v1, 1
	flat_atomic_add v1, v[2:3], v1 offset:1024 sc0
	v_cvt_f32_u32_e32 v2, v0
	v_sub_u32_e32 v3, 0, v0
	s_mov_b64 s[4:5], -1
	v_rcp_iflag_f32_e32 v2, v2
	s_nop 0
	v_mul_f32_e32 v2, 0x4f7ffffe, v2
	v_cvt_u32_f32_e32 v2, v2
	v_mul_lo_u32 v3, v3, v2
	v_mul_hi_u32 v3, v2, v3
	v_add_u32_e32 v2, v2, v3
	s_waitcnt vmcnt(0) lgkmcnt(0)
	v_mul_hi_u32 v2, v1, v2
	v_mul_lo_u32 v3, v2, v0
	v_sub_u32_e32 v3, v1, v3
	v_cmp_ge_u32_e32 vcc, v3, v0
	v_add_u32_e32 v4, 1, v2
	s_nop 0
	v_cndmask_b32_e32 v2, v2, v4, vcc
	v_sub_u32_e32 v4, v3, v0
	v_cndmask_b32_e32 v3, v3, v4, vcc
	v_cmp_ge_u32_e32 vcc, v3, v0
	v_add_u32_e32 v3, 1, v2
	s_nop 0
	v_cndmask_b32_e32 v2, v2, v3, vcc
	v_add_u32_e32 v3, 1, v1
	v_mad_u64_u32 v[0:1], s[0:1], v0, v2, v[0:1]
	s_add_u32 s0, s34, 0x3500
	s_addc_u32 s1, s35, 0
	v_cmp_ne_u32_e32 vcc, v3, v0
	v_mov_b64_e32 v[0:1], s[0:1]
	s_and_saveexec_b64 s[2:3], vcc
	s_cbranch_execz .LBB0_695
	v_mov_b64_e32 v[0:1], s[0:1]
	flat_load_dword v0, v[0:1] sc1
	s_mov_b64 s[8:9], 0
	s_waitcnt vmcnt(0) lgkmcnt(0)
	v_cmp_eq_u32_e32 vcc, v0, v2
	s_and_saveexec_b64 s[6:7], vcc
	s_cbranch_execz .LBB0_694
	s_add_u32 s4, s34, 0x200
	s_addc_u32 s5, s35, 0
	s_mov_b32 s21, 1
	s_branch .LBB0_687

; __device__ __forceinline__ unsigned xb_ld(unsigned* p)              { return __hip_atomic_load(p, __ATOMIC_RELAXED, __HIP_MEMORY_SCOPE_AGENT); }
; __device__ __forceinline__ unsigned xb_add(unsigned* p, unsigned v) { return __hip_atomic_fetch_add(p, v, __ATOMIC_RELAXED, __HIP_MEMORY_SCOPE_AGENT); }
; #define XB_SPIN(cond, bar) do { unsigned _sp = 0; while (cond) { __builtin_amdgcn_s_sleep(1); \
;     if ((++_sp & 255u) == 0u) { if (xb_ld(&(bar)[XB_TMO])) break; if (_sp > XB_SPIN_CAP) { atomicAdd(&(bar)[XB_TMO], 1u); break; } } } } while (0)
; __device__ __forceinline__ void xcd_barrier(const XcdBarrier& b) {
;     ...
;     if (threadIdx.x == 0) {
;         unsigned* bar = b.bar;
;         __builtin_amdgcn_s_waitcnt(0);
;         unsigned nloc = b.st[0], nx = b.st[1];
;         if (nloc == 0u) { xcd_barrier_complete(bar, b.x, nloc, nx); b.st[0] = nloc; b.st[1] = nx; }
;         const unsigned old = xb_add(&bar[XB_XSUB(b.x)], 1u);
;         const unsigned gen = old / nloc;
;         if (old + 1u == (gen + 1u) * nloc) {
;             __builtin_amdgcn_fence(__ATOMIC_RELEASE, "agent");
;             asm volatile("s_waitcnt vmcnt(0)" ::: "memory");
;             const unsigned og = xb_add(&bar[XB_TOP], 1u);
;             const unsigned tg = og / nx;
;             if (og + 1u == (tg + 1u) * nx) xb_add(&bar[XB_TOPGEN], 1u);
;             else XB_SPIN(xb_ld(&bar[XB_TOPGEN]) == tg, bar);
;             __builtin_amdgcn_fence(__ATOMIC_ACQUIRE, "agent");
;             xb_add(&bar[XB_XGEN(b.x)], 1u);
;             asm volatile("s_waitcnt vmcnt(0)" ::: "memory");
;         } else {
;             XB_SPIN(xb_ld(&bar[XB_XGEN(b.x)]) == gen, bar);
.LBB0_828:
	v_readlane_b32 s0, v255, 4
	s_lshl_b32 s22, s33, 6
	v_readlane_b32 s1, v255, 5
	s_mov_b32 s3, s1
	s_add_i32 s2, s22, 0x500
	v_writelane_b32 v255, s0, 4
	v_mov_b32_e32 v1, 1
	s_nop 0
	v_writelane_b32 v255, s1, 5
	s_lshl_b64 s[0:1], s[2:3], 2
	s_add_u32 s0, s36, s0
	s_addc_u32 s1, s37, s1
	v_mov_b64_e32 v[4:5], s[0:1]
	flat_atomic_add v3, v[4:5], v1 sc0
	v_cvt_f32_u32_e32 v1, v2
	v_sub_u32_e32 v4, 0, v2
	v_rcp_iflag_f32_e32 v1, v1
	s_nop 0
	v_mul_f32_e32 v1, 0x4f7ffffe, v1
	v_cvt_u32_f32_e32 v1, v1
	v_mul_lo_u32 v4, v4, v1
	v_mul_hi_u32 v4, v1, v4
	v_add_u32_e32 v1, v1, v4
	s_waitcnt vmcnt(0) lgkmcnt(0)
	v_mul_hi_u32 v1, v3, v1
	v_mul_lo_u32 v4, v1, v2
	v_sub_u32_e32 v4, v3, v4
	v_cmp_ge_u32_e32 vcc, v4, v2
	v_add_u32_e32 v5, 1, v1
	s_nop 0
	v_cndmask_b32_e32 v1, v1, v5, vcc
	v_sub_u32_e32 v5, v4, v2
	v_cndmask_b32_e32 v4, v4, v5, vcc
	v_cmp_ge_u32_e32 vcc, v4, v2
	v_add_u32_e32 v4, 1, v1
	s_nop 0
	v_cndmask_b32_e32 v1, v1, v4, vcc
	v_add_u32_e32 v4, 1, v3
	v_mad_u64_u32 v[2:3], s[0:1], v2, v1, v[2:3]
	v_cmp_ne_u32_e32 vcc, v4, v2
	s_and_saveexec_b64 s[0:1], vcc
	s_xor_b64 s[0:1], exec, s[0:1]
	s_cbranch_execz .LBB0_841
	buffer_inv sc1
	v_readlane_b32 s2, v255, 4
	v_readlane_b32 s3, v255, 5
	s_mov_b32 s7, s3
	s_add_i32 s6, s22, 0x900
	v_writelane_b32 v255, s2, 4
	s_nop 1
	v_writelane_b32 v255, s3, 5
	s_lshl_b64 s[2:3], s[6:7], 2
	s_add_u32 s6, s36, s2
	s_addc_u32 s7, s37, s3
	v_mov_b64_e32 v[2:3], s[6:7]
	flat_load_dword v0, v[2:3] sc1
	s_waitcnt vmcnt(0) lgkmcnt(0)
	v_cmp_eq_u32_e32 vcc, v0, v1
	s_and_saveexec_b64 s[2:3], vcc
	s_cbranch_execz .LBB0_840
	s_mov_b32 s23, 1
	s_mov_b64 s[8:9], 0
	s_branch .LBB0_832

; __device__ __forceinline__ unsigned xb_ld(unsigned* p)              { return __hip_atomic_load(p, __ATOMIC_RELAXED, __HIP_MEMORY_SCOPE_AGENT); }
; __device__ __forceinline__ unsigned xb_add(unsigned* p, unsigned v) { return __hip_atomic_fetch_add(p, v, __ATOMIC_RELAXED, __HIP_MEMORY_SCOPE_AGENT); }
; #define XB_SPIN(cond, bar) do { unsigned _sp = 0; while (cond) { __builtin_amdgcn_s_sleep(1); \
;     if ((++_sp & 255u) == 0u) { if (xb_ld(&(bar)[XB_TMO])) break; if (_sp > XB_SPIN_CAP) { atomicAdd(&(bar)[XB_TMO], 1u); break; } } } } while (0)
; __device__ __forceinline__ void xcd_barrier(const XcdBarrier& b) {
;     ...
;         if (old + 1u == (gen + 1u) * nloc) {
;             __builtin_amdgcn_fence(__ATOMIC_RELEASE, "agent");
;             asm volatile("s_waitcnt vmcnt(0)" ::: "memory");
;             const unsigned og = xb_add(&bar[XB_TOP], 1u);
;             const unsigned tg = og / nx;
;             if (og + 1u == (tg + 1u) * nx) xb_add(&bar[XB_TOPGEN], 1u);
;             else XB_SPIN(xb_ld(&bar[XB_TOPGEN]) == tg, bar);
.LBB0_841:
	s_andn2_saveexec_b64 s[0:1], s[0:1]
	s_cbranch_execz .LBB0_857
	v_mov_b32_e32 v1, s36
	v_add_co_u32_e32 v2, vcc, 0x3000, v1
	v_mov_b32_e32 v1, s37
	buffer_wbl2 sc1
	s_waitcnt vmcnt(0)
	buffer_inv sc1
	v_addc_co_u32_e32 v3, vcc, 0, v1, vcc
	v_mov_b32_e32 v1, 1
	flat_atomic_add v1, v[2:3], v1 offset:1024 sc0
	v_cvt_f32_u32_e32 v2, v0
	v_sub_u32_e32 v3, 0, v0
	s_mov_b64 s[6:7], -1
	v_rcp_iflag_f32_e32 v2, v2
	s_nop 0
	v_mul_f32_e32 v2, 0x4f7ffffe, v2
	v_cvt_u32_f32_e32 v2, v2
	v_mul_lo_u32 v3, v3, v2
	v_mul_hi_u32 v3, v2, v3
	v_add_u32_e32 v2, v2, v3
	s_waitcnt vmcnt(0) lgkmcnt(0)
	v_mul_hi_u32 v2, v1, v2
	v_mul_lo_u32 v3, v2, v0
	v_sub_u32_e32 v3, v1, v3
	v_cmp_ge_u32_e32 vcc, v3, v0
	v_add_u32_e32 v4, 1, v2
	s_nop 0
	v_cndmask_b32_e32 v2, v2, v4, vcc
	v_sub_u32_e32 v4, v3, v0
	v_cndmask_b32_e32 v3, v3, v4, vcc
	v_cmp_ge_u32_e32 vcc, v3, v0
	v_add_u32_e32 v3, 1, v2
	s_nop 0
	v_cndmask_b32_e32 v2, v2, v3, vcc
	v_add_u32_e32 v3, 1, v1
	v_mad_u64_u32 v[0:1], s[0:1], v0, v2, v[0:1]
	s_add_u32 s0, s36, 0x3500
	s_addc_u32 s1, s37, 0
	v_cmp_ne_u32_e32 vcc, v3, v0
	v_mov_b64_e32 v[0:1], s[0:1]
	s_and_saveexec_b64 s[2:3], vcc
	s_cbranch_execz .LBB0_854
	v_mov_b64_e32 v[0:1], s[0:1]
	flat_load_dword v0, v[0:1] sc1
	s_mov_b64 s[10:11], 0
	s_waitcnt vmcnt(0) lgkmcnt(0)
	v_cmp_eq_u32_e32 vcc, v0, v2
	s_and_saveexec_b64 s[8:9], vcc
	s_cbranch_execz .LBB0_853
	s_add_u32 s6, s36, 0x200
	s_addc_u32 s7, s37, 0
	s_mov_b32 s23, 1
	s_branch .LBB0_846

; __device__ __forceinline__ unsigned xb_add(unsigned* p, unsigned v) { return __hip_atomic_fetch_add(p, v, __ATOMIC_RELAXED, __HIP_MEMORY_SCOPE_AGENT); }
; __device__ __forceinline__ void xcd_barrier(const XcdBarrier& b) {
;     ...
;             __builtin_amdgcn_fence(__ATOMIC_ACQUIRE, "agent");
;             xb_add(&bar[XB_XGEN(b.x)], 1u);
;             asm volatile("s_waitcnt vmcnt(0)" ::: "memory");
.LBB0_856:
	s_or_b64 exec, exec, s[0:1]
	v_readlane_b32 s0, v255, 4
	v_readlane_b32 s1, v255, 5
	s_mov_b32 s3, s1
	s_add_i32 s2, s22, 0x900
	v_writelane_b32 v255, s0, 4
	v_mov_b32_e32 v2, 1
	s_waitcnt vmcnt(0) lgkmcnt(0)
	v_writelane_b32 v255, s1, 5
	s_lshl_b64 s[0:1], s[2:3], 2
	s_add_u32 s0, s36, s0
	s_addc_u32 s1, s37, s1
	v_mov_b64_e32 v[0:1], s[0:1]
	flat_atomic_add v[0:1], v2
	s_waitcnt vmcnt(0)

; __device__ __forceinline__ unsigned xb_ld(unsigned* p)              { return __hip_atomic_load(p, __ATOMIC_RELAXED, __HIP_MEMORY_SCOPE_AGENT); }
; __device__ __forceinline__ unsigned xb_add(unsigned* p, unsigned v) { return __hip_atomic_fetch_add(p, v, __ATOMIC_RELAXED, __HIP_MEMORY_SCOPE_AGENT); }
; #define XB_SPIN(cond, bar) do { unsigned _sp = 0; while (cond) { __builtin_amdgcn_s_sleep(1); \
;     if ((++_sp & 255u) == 0u) { if (xb_ld(&(bar)[XB_TMO])) break; if (_sp > XB_SPIN_CAP) { atomicAdd(&(bar)[XB_TMO], 1u); break; } } } } while (0)
; __device__ __forceinline__ void xcd_barrier(const XcdBarrier& b) {
;     ...
;         if (old + 1u == (gen + 1u) * nloc) {
;             __builtin_amdgcn_fence(__ATOMIC_RELEASE, "agent");
;             asm volatile("s_waitcnt vmcnt(0)" ::: "memory");
;             const unsigned og = xb_add(&bar[XB_TOP], 1u);
;             const unsigned tg = og / nx;
;             if (og + 1u == (tg + 1u) * nx) xb_add(&bar[XB_TOPGEN], 1u);
;             else XB_SPIN(xb_ld(&bar[XB_TOPGEN]) == tg, bar);
.LBB0_1365:
	v_mov_b32_e32 v1, s34
	v_add_co_u32_e32 v2, vcc, 0x3000, v1
	v_mov_b32_e32 v1, s35
	buffer_wbl2 sc1
	s_waitcnt vmcnt(0)
	buffer_inv sc1
	v_addc_co_u32_e32 v3, vcc, 0, v1, vcc
	v_mov_b32_e32 v1, 1
	flat_atomic_add v1, v[2:3], v1 offset:1024 sc0
	v_cvt_f32_u32_e32 v2, v0
	v_sub_u32_e32 v3, 0, v0
	s_mov_b64 s[4:5], -1
	v_rcp_iflag_f32_e32 v2, v2
	s_nop 0
	v_mul_f32_e32 v2, 0x4f7ffffe, v2
	v_cvt_u32_f32_e32 v2, v2
	v_mul_lo_u32 v3, v3, v2
	v_mul_hi_u32 v3, v2, v3
	v_add_u32_e32 v2, v2, v3
	s_waitcnt vmcnt(0) lgkmcnt(0)
	v_mul_hi_u32 v2, v1, v2
	v_mul_lo_u32 v3, v2, v0
	v_sub_u32_e32 v3, v1, v3
	v_cmp_ge_u32_e32 vcc, v3, v0
	v_add_u32_e32 v4, 1, v2
	s_nop 0
	v_cndmask_b32_e32 v2, v2, v4, vcc
	v_sub_u32_e32 v4, v3, v0
	v_cndmask_b32_e32 v3, v3, v4, vcc
	v_cmp_ge_u32_e32 vcc, v3, v0
	v_add_u32_e32 v3, 1, v2
	s_nop 0
	v_cndmask_b32_e32 v2, v2, v3, vcc
	v_add_u32_e32 v3, 1, v1
	v_mad_u64_u32 v[0:1], s[0:1], v0, v2, v[0:1]
	s_add_u32 s0, s34, 0x3500
	s_addc_u32 s1, s35, 0
	v_cmp_ne_u32_e32 vcc, v3, v0
	v_mov_b64_e32 v[0:1], s[0:1]
	s_and_saveexec_b64 s[2:3], vcc
	s_cbranch_execz .LBB0_1377
	v_mov_b64_e32 v[0:1], s[0:1]
	flat_load_dword v0, v[0:1] sc1
	s_mov_b64 s[8:9], 0
	s_waitcnt vmcnt(0) lgkmcnt(0)
	v_cmp_eq_u32_e32 vcc, v0, v2
	s_and_saveexec_b64 s[6:7], vcc
	s_cbranch_execz .LBB0_1376
	s_add_u32 s4, s34, 0x200
	s_addc_u32 s5, s35, 0
	s_mov_b32 s21, 1
	s_branch .LBB0_1369
